# speedup vs baseline: 1.0139x; 1.0018x over previous
; __device__ __forceinline__ float bflo(unsigned v) { return __uint_as_float(v << 16); }
; __device__ __forceinline__ float bfhi(unsigned v) { return __uint_as_float(v & 0xffff0000u); }
; __device__ __forceinline__ void ret_stepC(const Params& p, unsigned char* smem, int u) {
;     ...
;     __syncthreads();
; #pragma unroll
;     for (int m = 0; m < 4; ++m) {
;         const int c = wr * 64 + m * 16 + fr; float s = 0.f, s2 = 0.f;
; #pragma unroll
;         for (int w = 0; w < 4; ++w) { s += red[(c * 4 + w) * 2]; s2 += red[(c * 4 + w) * 2 + 1]; }
;         mean[m] = s * (1.0f / 128.0f); const float var = fmaxf(s2 * (1.0f / 128.0f) - mean[m] * mean[m], 0.f); rstd[m] = rsqrtf(var + 1e-6f);
;     }
;     bf16_t* yb = (bf16_t*)(p.ws + WS_Y) + tok0 * DM;
; #pragma unroll
;     for (int m = 0; m < 4; ++m)
; #pragma unroll
;         for (int nn = 0; nn < 2; ++nn) {
;             const int c = wr * 64 + m * 16 + fr, e = wc * 32 + nn * 16 + fq * 4;
;             const u32x2 graw = *(const u32x2*)(proj + (size_t)c * INP + C_RG + h * 128 + e);
;             const f32x4 beta = *(const f32x4*)(p.ret_beta + h * 128 + e);
;             const float g[4] = {bflo(graw.x), bfhi(graw.x), bflo(graw.y), bfhi(graw.y)};
;             float y[4];
; #pragma unroll
;             for (int j = 0; j < 4; ++j) { const float on = (a1[m][nn][j] - mean[m]) * rstd[m]; const float sg = g[j] / (1.0f + __expf(-g[j])); y[j] = sg * (on * beta[j]); }
.LBB0_1721:
	s_or_b64 exec, exec, s[8:9]
	s_lshl_b64 s[4:5], s[62:63], 12
	s_add_u32 s14, s86, s4
	s_addc_u32 s15, s87, s5
	s_lshl_b32 s4, s10, 2
	s_add_u32 s12, s56, s4
	v_mov_b64_e32 v[44:45], s[60:61]
	s_addc_u32 s13, s57, 0
	s_lshl_b32 s36, s10, 1
	v_mad_i64_i32 v[0:1], s[4:5], v56, s64, v[44:45]
	v_lshl_add_u64 v[0:1], v[0:1], 0, s[36:37]
	v_lshl_add_u64 v[76:77], v[0:1], 0, v[48:49]
	v_add_co_u32_e32 v0, vcc, s80, v76
	s_waitcnt lgkmcnt(0)
	s_nop 0
	v_addc_co_u32_e32 v1, vcc, 0, v77, vcc
	s_barrier
	v_lshlrev_b32_e32 v25, 2, v51
	s_mov_b32 s98, 0x36000
	s_mov_b32 s99, 0
	global_load_dwordx2 v[132:133], v[0:1], off offset:2048
	global_load_dwordx2 v[134:135], v[0:1], off offset:2080
	v_lshl_add_u64 v[148:149], v[0:1], 0, s[98:99]
	global_load_dwordx2 v[136:137], v[148:149], off offset:2048
	global_load_dwordx2 v[138:139], v[148:149], off offset:2080
	v_lshl_add_u64 v[150:151], v[148:149], 0, s[98:99]
	global_load_dwordx2 v[140:141], v[150:151], off offset:2048
	global_load_dwordx2 v[142:143], v[150:151], off offset:2080
	v_lshl_add_u64 v[152:153], v[150:151], 0, s[98:99]
	global_load_dwordx2 v[144:145], v[152:153], off offset:2048
	global_load_dwordx2 v[146:147], v[152:153], off offset:2080
	global_load_dwordx4 v[156:159], v25, s[12:13]
	global_load_dwordx4 v[160:163], v25, s[12:13] offset:64
	v_lshl_add_u32 v0, v56, 5, 0
	ds_read_b128 v[86:89], v0
	ds_read_b128 v[90:93], v0 offset:16
	ds_read_b128 v[20:23], v0 offset:512
	ds_read_b128 v[16:19], v0 offset:528
	ds_read_b128 v[12:15], v0 offset:1024
	ds_read_b128 v[8:11], v0 offset:1040
	ds_read_b128 v[4:7], v0 offset:1536
	ds_read_b128 v[0:3], v0 offset:1552
	s_waitcnt lgkmcnt(7)
	v_pk_add_f32 v[86:87], v[86:87], 0 op_sel_hi:[1,0]
	s_add_u32 s14, s14, s36
	v_pk_add_f32 v[86:87], v[86:87], v[88:89]
	v_lshl_add_u64 v[88:89], v[76:77], 0, s[42:43]
	s_waitcnt lgkmcnt(6)
	v_pk_add_f32 v[76:77], v[86:87], v[90:91]
	s_addc_u32 s15, s15, 0
	v_pk_add_f32 v[76:77], v[76:77], v[92:93]
	s_waitcnt lgkmcnt(5)
	v_pk_add_f32 v[20:21], v[20:21], 0 op_sel_hi:[1,0]
	v_pk_mul_f32 v[76:77], v[76:77], s[40:41] op_sel_hi:[1,0]
	v_pk_add_f32 v[20:21], v[20:21], v[22:23]
	v_fma_f32 v26, -v76, v76, v77
	v_max_f32_e32 v26, 0, v26
	v_add_f32_e32 v26, 0x358637bd, v26
	v_mul_f32_e32 v29, 0x4b800000, v26
	v_cmp_gt_f32_e32 vcc, s79, v26
	v_sub_f32_e32 v36, v74, v76
	v_sub_f32_e32 v39, v75, v76
	v_cndmask_b32_e32 v26, v26, v29, vcc
	v_rsq_f32_e32 v26, v26
	v_sub_f32_e32 v29, v81, v76
	s_waitcnt lgkmcnt(4)
	v_pk_add_f32 v[16:17], v[20:21], v[16:17]
	s_waitcnt lgkmcnt(3)
	v_pk_add_f32 v[12:13], v[12:13], 0 op_sel_hi:[1,0]
	v_mul_f32_e32 v51, 0x45800000, v26
	v_cndmask_b32_e32 v26, v26, v51, vcc
	v_mul_f32_e32 v36, v36, v26
	v_mul_f32_e32 v29, v29, v26
	v_mul_f32_e32 v39, v39, v26
	v_pk_add_f32 v[16:17], v[16:17], v[18:19]
	v_pk_add_f32 v[12:13], v[12:13], v[14:15]
	v_pk_mul_f32 v[16:17], v[16:17], s[40:41] op_sel_hi:[1,0]
	s_waitcnt lgkmcnt(2)
	v_pk_add_f32 v[8:9], v[12:13], v[8:9]
	v_fma_f32 v17, -v16, v16, v17
	v_max_f32_e32 v17, 0, v17
	v_add_f32_e32 v17, 0x358637bd, v17
	v_mul_f32_e32 v18, 0x4b800000, v17
	v_sub_f32_e32 v19, v64, v16
	v_sub_f32_e32 v20, v65, v16
	v_pk_add_f32 v[8:9], v[8:9], v[10:11]
	s_waitcnt lgkmcnt(1)
	v_pk_add_f32 v[4:5], v[4:5], 0 op_sel_hi:[1,0]
	v_pk_mul_f32 v[8:9], v[8:9], s[40:41] op_sel_hi:[1,0]
	v_pk_add_f32 v[4:5], v[4:5], v[6:7]
	v_fma_f32 v9, -v8, v8, v9
	v_max_f32_e32 v9, 0, v9
	v_add_f32_e32 v9, 0x358637bd, v9
	v_mul_f32_e32 v10, 0x4b800000, v9
	v_sub_f32_e32 v12, v47, v8
	v_sub_f32_e32 v13, v42, v8
	s_waitcnt lgkmcnt(0)
	v_pk_add_f32 v[0:1], v[4:5], v[0:1]
	s_add_i32 s88, s88, s44
	v_pk_add_f32 v[0:1], v[0:1], v[2:3]
	s_add_i32 s83, s83, s68
	v_pk_mul_f32 v[0:1], v[0:1], s[40:41] op_sel_hi:[1,0]
	s_add_i32 s82, s82, s73
	v_fma_f32 v1, -v0, v0, v1
	v_max_f32_e32 v1, 0, v1
	v_add_f32_e32 v1, 0x358637bd, v1
	v_mul_f32_e32 v2, 0x4b800000, v1
	v_sub_f32_e32 v4, v35, v0
	v_sub_f32_e32 v5, v32, v0
	s_add_u32 s58, s58, s34
	s_addc_u32 s59, s59, s35
	s_cmpk_gt_i32 s88, 0x7ff
	s_waitcnt vmcnt(0)
	v_mov_b64_e32 v[94:95], v[132:133]
	v_mov_b64_e32 v[82:83], v[156:157]
	v_mov_b64_e32 v[84:85], v[158:159]
	v_lshlrev_b32_e32 v51, 16, v94
	v_and_b32_e32 v55, 0xffff0000, v94
	v_mul_f32_e32 v61, 0xbfb8aa3b, v51
	v_mul_f32_e32 v67, 0xbfb8aa3b, v55
	v_exp_f32_e32 v61, v61
	v_lshlrev_b32_e32 v57, 16, v95
	v_exp_f32_e32 v67, v67
	v_mul_f32_e32 v68, 0xbfb8aa3b, v57
	v_exp_f32_e32 v68, v68
	v_add_f32_e32 v61, 1.0, v61
	v_add_f32_e32 v67, 1.0, v67
	v_div_scale_f32 v74, s[4:5], v61, v61, v51
	v_mul_f32_e32 v36, v36, v83
	v_div_scale_f32 v77, s[4:5], v67, v67, v55
	v_rcp_f32_e32 v83, v74
	v_add_f32_e32 v68, 1.0, v68
	v_rcp_f32_e32 v86, v77
	v_mul_f32_e32 v29, v29, v82
	v_div_scale_f32 v82, s[4:5], v68, v68, v57
	v_rcp_f32_e32 v87, v82
	v_fma_f32 v91, -v74, v83, 1.0
	v_div_scale_f32 v75, vcc, v51, v61, v51
	v_fma_f32 v92, -v77, v86, 1.0
	v_fmac_f32_e32 v83, v91, v83
	v_div_scale_f32 v81, s[8:9], v55, v67, v55
	v_fmac_f32_e32 v86, v92, v86
	v_mul_f32_e32 v91, v75, v83
	v_and_b32_e32 v58, 0xffff0000, v95
	v_fma_f32 v93, -v82, v87, 1.0
	v_mul_f32_e32 v92, v81, v86
	v_fma_f32 v94, -v74, v91, v75
	v_mul_f32_e32 v71, 0xbfb8aa3b, v58
	v_div_scale_f32 v90, s[10:11], v57, v68, v57
	v_fmac_f32_e32 v87, v93, v87
	v_fma_f32 v95, -v77, v92, v81
	v_fmac_f32_e32 v91, v94, v83
	v_exp_f32_e32 v71, v71
	v_mul_f32_e32 v93, v90, v87
	v_fmac_f32_e32 v92, v95, v86
	v_fma_f32 v74, -v74, v91, v75
	v_fma_f32 v96, -v82, v93, v90
	v_fma_f32 v75, -v77, v92, v81
	v_div_fmas_f32 v74, v74, v83, v91
	s_mov_b64 vcc, s[8:9]
	v_fmac_f32_e32 v93, v96, v87
	v_div_fixup_f32 v51, v74, v61, v51
	v_div_fmas_f32 v61, v75, v86, v92
; __device__ __forceinline__ unsigned cvt_pk_bf16(float lo, float hi) { unsigned r; asm volatile("v_cvt_pk_bf16_f32 %0, %1, %2" : "=v"(r) : "v"(lo), "v"(hi)); return r; }
; __device__ __forceinline__ float bflo(unsigned v) { return __uint_as_float(v << 16); }
; __device__ __forceinline__ float bfhi(unsigned v) { return __uint_as_float(v & 0xffff0000u); }
; __device__ __forceinline__ void ret_stepC(const Params& p, unsigned char* smem, int u) {
;     ...
;     bf16_t* yb = (bf16_t*)(p.ws + WS_Y) + tok0 * DM;
; #pragma unroll
;     for (int m = 0; m < 4; ++m)
; #pragma unroll
;         for (int nn = 0; nn < 2; ++nn) {
;             const int c = wr * 64 + m * 16 + fr, e = wc * 32 + nn * 16 + fq * 4;
;             const u32x2 graw = *(const u32x2*)(proj + (size_t)c * INP + C_RG + h * 128 + e);
;             const f32x4 beta = *(const f32x4*)(p.ret_beta + h * 128 + e);
;             const float g[4] = {bflo(graw.x), bfhi(graw.x), bflo(graw.y), bfhi(graw.y)};
;             float y[4];
; #pragma unroll
;             for (int j = 0; j < 4; ++j) { const float on = (a1[m][nn][j] - mean[m]) * rstd[m]; const float sg = g[j] / (1.0f + __expf(-g[j])); y[j] = sg * (on * beta[j]); }
;             u32x2 w; w.x = cvt_pk_bf16(y[0], y[1]); w.y = cvt_pk_bf16(y[2], y[3]);
;             *(u32x2*)(yb + (size_t)c * DM + h * 128 + e) = w;
	v_fma_f32 v77, -v82, v93, v90
	v_mul_f32_e32 v29, v29, v51
	v_div_fixup_f32 v51, v61, v67, v55
	s_mov_b64 vcc, s[10:11]
	v_mul_f32_e32 v36, v36, v51
	v_div_fmas_f32 v51, v77, v87, v93
	v_add_f32_e32 v55, 1.0, v71
	v_div_fixup_f32 v51, v51, v68, v57
	v_div_scale_f32 v57, s[4:5], v55, v55, v58
	v_rcp_f32_e32 v61, v57
	v_mul_f32_e32 v39, v39, v84
	v_mul_f32_e32 v39, v39, v51
	v_sub_f32_e32 v51, v73, v76
	v_fma_f32 v67, -v57, v61, 1.0
	v_fmac_f32_e32 v61, v67, v61
	v_div_scale_f32 v67, vcc, v58, v55, v58
	v_mul_f32_e32 v68, v67, v61
	v_fma_f32 v71, -v57, v68, v67
	v_fmac_f32_e32 v68, v71, v61
	v_fma_f32 v57, -v57, v68, v67
	v_mul_f32_e32 v51, v51, v26
	v_div_fmas_f32 v57, v57, v61, v68
	v_div_fixup_f32 v55, v57, v55, v58
	v_mul_f32_e32 v51, v51, v85
	v_mul_f32_e32 v51, v51, v55
	v_cvt_pk_bf16_f32 v74, v29, v36
	v_cvt_pk_bf16_f32 v75, v39, v51
	v_mov_b64_e32 v[86:87], v[134:135]
	v_ashrrev_i32_e32 v57, 31, v56
	v_lshlrev_b64 v[56:57], 12, v[56:57]
	v_lshl_add_u64 v[56:57], s[14:15], 0, v[56:57]
	v_lshl_add_u64 v[56:57], v[56:57], 0, v[48:49]
	global_store_dwordx2 v[56:57], v[74:75], off
	v_mov_b64_e32 v[82:83], v[160:161]
	v_mov_b64_e32 v[84:85], v[162:163]
	v_sub_f32_e32 v39, v69, v76
	v_sub_f32_e32 v29, v72, v76
	v_mul_f32_e32 v29, v29, v26
	v_mul_f32_e32 v39, v39, v26
	v_sub_f32_e32 v36, v70, v76
	v_mul_f32_e32 v36, v36, v26
	v_lshlrev_b32_e32 v51, 16, v86
	v_and_b32_e32 v55, 0xffff0000, v86
	v_mul_f32_e32 v67, 0xbfb8aa3b, v51
	v_lshlrev_b32_e32 v58, 16, v87
	v_mul_f32_e32 v68, 0xbfb8aa3b, v55
	v_exp_f32_e32 v67, v67
	v_mul_f32_e32 v69, 0xbfb8aa3b, v58
	v_exp_f32_e32 v68, v68
	v_exp_f32_e32 v69, v69
	v_add_f32_e32 v67, 1.0, v67
	v_div_scale_f32 v71, s[4:5], v67, v67, v51
	v_add_f32_e32 v68, 1.0, v68
	v_add_f32_e32 v69, 1.0, v69
	v_div_scale_f32 v73, s[4:5], v68, v68, v55
	v_rcp_f32_e32 v77, v71
	v_div_scale_f32 v75, s[4:5], v69, v69, v58
	v_rcp_f32_e32 v81, v73
	v_mul_f32_e32 v29, v29, v82
	v_rcp_f32_e32 v82, v75
	v_mul_f32_e32 v39, v39, v84
	v_fma_f32 v84, -v71, v77, 1.0
	v_div_scale_f32 v72, vcc, v51, v67, v51
	v_fma_f32 v86, -v73, v81, 1.0
	v_fmac_f32_e32 v77, v84, v77
	v_and_b32_e32 v61, 0xffff0000, v87
	v_div_scale_f32 v74, s[8:9], v55, v68, v55
	v_fma_f32 v87, -v75, v82, 1.0
	v_fmac_f32_e32 v81, v86, v81
	v_mul_f32_e32 v84, v72, v77
	v_mul_f32_e32 v70, 0xbfb8aa3b, v61
	v_mul_f32_e32 v36, v36, v83
	v_div_scale_f32 v83, s[10:11], v58, v69, v58
	v_fmac_f32_e32 v82, v87, v82
	v_mul_f32_e32 v86, v74, v81
	v_fma_f32 v88, -v71, v84, v72
	v_exp_f32_e32 v70, v70
	v_mul_f32_e32 v87, v83, v82
	v_fma_f32 v89, -v73, v86, v74
	v_fmac_f32_e32 v84, v88, v77
	v_fma_f32 v90, -v75, v87, v83
	v_fmac_f32_e32 v86, v89, v81
	v_fma_f32 v71, -v71, v84, v72
	v_fmac_f32_e32 v87, v90, v82
	v_fma_f32 v72, -v73, v86, v74
	v_div_fmas_f32 v71, v71, v77, v84
	s_mov_b64 vcc, s[8:9]
	v_fma_f32 v73, -v75, v87, v83
	v_div_fixup_f32 v51, v71, v67, v51
	v_div_fmas_f32 v67, v72, v81, v86
	s_mov_b64 vcc, s[10:11]
	v_add_f32_e32 v70, 1.0, v70
	v_mul_f32_e32 v29, v29, v51
	v_div_fixup_f32 v51, v67, v68, v55
	v_div_fmas_f32 v55, v73, v82, v87
	v_mul_f32_e32 v36, v36, v51
	v_div_fixup_f32 v51, v55, v69, v58
	v_div_scale_f32 v55, s[4:5], v70, v70, v61
	v_rcp_f32_e32 v58, v55
	v_mul_f32_e32 v39, v39, v51
	v_sub_f32_e32 v51, v66, v76
	v_mul_f32_e32 v26, v51, v26
	v_fma_f32 v51, -v55, v58, 1.0
	v_fmac_f32_e32 v58, v51, v58
	v_div_scale_f32 v51, vcc, v61, v70, v61
	v_mul_f32_e32 v66, v51, v58
	v_fma_f32 v67, -v55, v66, v51
	v_fmac_f32_e32 v66, v67, v58
	v_fma_f32 v51, -v55, v66, v51
	v_mad_i64_i32 v[68:69], s[4:5], v52, s64, v[44:45]
	v_div_fmas_f32 v51, v51, v58, v66
	v_lshl_add_u64 v[68:69], v[68:69], 0, s[36:37]
	v_div_fixup_f32 v51, v51, v70, v61
	v_lshl_add_u64 v[70:71], v[68:69], 0, v[48:49]
	v_add_co_u32_e32 v68, vcc, s80, v70
	v_mul_f32_e32 v26, v26, v85
	s_nop 0
	v_addc_co_u32_e32 v69, vcc, 0, v71, vcc
	v_mul_f32_e32 v26, v26, v51
	v_cvt_pk_bf16_f32 v66, v29, v36
	v_cvt_pk_bf16_f32 v67, v39, v26
	v_mov_b64_e32 v[72:73], v[136:137]
	v_cmp_gt_f32_e32 vcc, s79, v17
	global_store_dwordx2 v[56:57], v[66:67], off offset:32
	v_mov_b64_e32 v[66:67], v[156:157]
	v_mov_b64_e32 v[68:69], v[158:159]
	v_cndmask_b32_e32 v17, v17, v18, vcc
	v_rsq_f32_e32 v17, v17
	v_sub_f32_e32 v18, v53, v16
	v_lshl_add_u64 v[22:23], v[70:71], 0, s[42:43]
	v_mul_f32_e32 v21, 0x45800000, v17
	v_cndmask_b32_e32 v17, v17, v21, vcc
	v_mul_f32_e32 v19, v19, v17
	v_mul_f32_e32 v18, v18, v17
	v_mul_f32_e32 v20, v20, v17
	v_lshlrev_b32_e32 v21, 16, v72
	v_and_b32_e32 v26, 0xffff0000, v72
	v_mul_f32_e32 v39, 0xbfb8aa3b, v21
	v_lshlrev_b32_e32 v29, 16, v73
	v_mul_f32_e32 v51, 0xbfb8aa3b, v26
	v_exp_f32_e32 v39, v39
	v_mul_f32_e32 v53, 0xbfb8aa3b, v29
	v_exp_f32_e32 v51, v51
	v_exp_f32_e32 v53, v53
	v_add_f32_e32 v39, 1.0, v39
	v_div_scale_f32 v55, s[4:5], v39, v39, v21
	v_add_f32_e32 v51, 1.0, v51
	v_add_f32_e32 v53, 1.0, v53
	v_div_scale_f32 v57, s[4:5], v51, v51, v26
	v_rcp_f32_e32 v61, v55
	v_div_scale_f32 v58, s[4:5], v53, v53, v29
	v_rcp_f32_e32 v64, v57
	v_rcp_f32_e32 v65, v58
	v_mul_f32_e32 v19, v19, v67
	v_fma_f32 v67, -v55, v61, 1.0
	v_div_scale_f32 v56, vcc, v21, v39, v21
	v_fma_f32 v70, -v57, v64, 1.0
	v_fmac_f32_e32 v61, v67, v61
	v_mul_f32_e32 v18, v18, v66
	v_div_scale_f32 v66, s[8:9], v26, v51, v26
	v_fma_f32 v71, -v58, v65, 1.0
	v_fmac_f32_e32 v64, v70, v64
	v_mul_f32_e32 v67, v56, v61
	v_fmac_f32_e32 v65, v71, v65
	v_mul_f32_e32 v70, v66, v64
	v_fma_f32 v71, -v55, v67, v56
	v_fma_f32 v72, -v57, v70, v66
	v_fmac_f32_e32 v67, v71, v61
	v_fmac_f32_e32 v70, v72, v64
	v_fma_f32 v55, -v55, v67, v56
	v_fma_f32 v56, -v57, v70, v66
	v_div_fmas_f32 v55, v55, v61, v67
	s_mov_b64 vcc, s[8:9]
; __device__ __forceinline__ unsigned cvt_pk_bf16(float lo, float hi) { unsigned r; asm volatile("v_cvt_pk_bf16_f32 %0, %1, %2" : "=v"(r) : "v"(lo), "v"(hi)); return r; }
; __device__ __forceinline__ float bflo(unsigned v) { return __uint_as_float(v << 16); }
; __device__ __forceinline__ float bfhi(unsigned v) { return __uint_as_float(v & 0xffff0000u); }
; __device__ __forceinline__ void ret_stepC(const Params& p, unsigned char* smem, int u) {
;     ...
;     bf16_t* yb = (bf16_t*)(p.ws + WS_Y) + tok0 * DM;
; #pragma unroll
;     for (int m = 0; m < 4; ++m)
; #pragma unroll
;         for (int nn = 0; nn < 2; ++nn) {
;             const int c = wr * 64 + m * 16 + fr, e = wc * 32 + nn * 16 + fq * 4;
;             const u32x2 graw = *(const u32x2*)(proj + (size_t)c * INP + C_RG + h * 128 + e);
;             const f32x4 beta = *(const f32x4*)(p.ret_beta + h * 128 + e);
;             const float g[4] = {bflo(graw.x), bfhi(graw.x), bflo(graw.y), bfhi(graw.y)};
;             float y[4];
; #pragma unroll
;             for (int j = 0; j < 4; ++j) { const float on = (a1[m][nn][j] - mean[m]) * rstd[m]; const float sg = g[j] / (1.0f + __expf(-g[j])); y[j] = sg * (on * beta[j]); }
;             u32x2 w; w.x = cvt_pk_bf16(y[0], y[1]); w.y = cvt_pk_bf16(y[2], y[3]);
;             *(u32x2*)(yb + (size_t)c * DM + h * 128 + e) = w;
	v_div_fixup_f32 v21, v55, v39, v21
	v_div_fmas_f32 v39, v56, v64, v70
	v_mul_f32_e32 v18, v18, v21
	v_div_fixup_f32 v21, v39, v51, v26
	v_mul_f32_e32 v19, v19, v21
	v_div_scale_f32 v21, vcc, v29, v53, v29
	v_mul_f32_e32 v26, v21, v65
	v_and_b32_e32 v36, 0xffff0000, v73
	v_fma_f32 v39, -v58, v26, v21
	v_fmac_f32_e32 v26, v39, v65
	v_mul_f32_e32 v39, 0xbfb8aa3b, v36
	v_exp_f32_e32 v39, v39
	v_fma_f32 v21, -v58, v26, v21
	v_div_fmas_f32 v21, v21, v65, v26
	v_div_fixup_f32 v21, v21, v53, v29
	v_add_f32_e32 v26, 1.0, v39
	v_div_scale_f32 v29, s[4:5], v26, v26, v36
	v_rcp_f32_e32 v39, v29
	v_mul_f32_e32 v20, v20, v68
	v_mul_f32_e32 v20, v20, v21
	v_sub_f32_e32 v21, v63, v16
	v_fma_f32 v51, -v29, v39, 1.0
	v_fmac_f32_e32 v39, v51, v39
	v_div_scale_f32 v51, vcc, v36, v26, v36
	v_mul_f32_e32 v53, v51, v39
	v_fma_f32 v55, -v29, v53, v51
	v_fmac_f32_e32 v53, v55, v39
	v_fma_f32 v29, -v29, v53, v51
	v_mul_f32_e32 v21, v21, v17
	v_div_fmas_f32 v29, v29, v39, v53
	v_div_fixup_f32 v26, v29, v26, v36
	v_mul_f32_e32 v21, v21, v69
	v_mul_f32_e32 v21, v21, v26
	v_ashrrev_i32_e32 v53, 31, v52
	v_cvt_pk_bf16_f32 v18, v18, v19
	v_cvt_pk_bf16_f32 v19, v20, v21
	v_lshlrev_b64 v[20:21], 12, v[52:53]
	v_mov_b64_e32 v[22:23], v[138:139]
	v_lshl_add_u64 v[20:21], s[14:15], 0, v[20:21]
	v_lshl_add_u64 v[52:53], v[20:21], 0, v[48:49]
	global_store_dwordx2 v[52:53], v[18:19], off
	v_mov_b64_e32 v[18:19], v[160:161]
	v_mov_b64_e32 v[20:21], v[162:163]
	v_sub_f32_e32 v26, v62, v16
	v_mul_f32_e32 v26, v26, v17
	v_sub_f32_e32 v29, v60, v16
	v_mul_f32_e32 v29, v29, v17
	v_sub_f32_e32 v36, v59, v16
	v_mul_f32_e32 v36, v36, v17
	v_sub_f32_e32 v16, v46, v16
	v_mul_f32_e32 v16, v16, v17
	v_lshlrev_b32_e32 v39, 16, v22
	v_and_b32_e32 v22, 0xffff0000, v22
	v_mul_f32_e32 v55, 0xbfb8aa3b, v39
	v_mul_f32_e32 v56, 0xbfb8aa3b, v22
	v_exp_f32_e32 v55, v55
	v_lshlrev_b32_e32 v51, 16, v23
	v_mul_f32_e32 v18, v26, v18
	v_exp_f32_e32 v26, v56
	v_mul_f32_e32 v57, 0xbfb8aa3b, v51
	v_mul_f32_e32 v19, v29, v19
	v_exp_f32_e32 v29, v57
	v_add_f32_e32 v55, 1.0, v55
	v_add_f32_e32 v26, 1.0, v26
	v_div_scale_f32 v57, s[4:5], v55, v55, v39
	v_div_scale_f32 v59, s[4:5], v26, v26, v22
	v_rcp_f32_e32 v62, v57
	v_add_f32_e32 v29, 1.0, v29
	v_rcp_f32_e32 v63, v59
	v_div_scale_f32 v61, s[4:5], v29, v29, v51
	v_and_b32_e32 v23, 0xffff0000, v23
	v_rcp_f32_e32 v64, v61
	v_mul_f32_e32 v58, 0xbfb8aa3b, v23
	v_fma_f32 v66, -v57, v62, 1.0
	v_exp_f32_e32 v56, v58
	v_div_scale_f32 v58, vcc, v39, v55, v39
	v_fma_f32 v67, -v59, v63, 1.0
	v_fmac_f32_e32 v62, v66, v62
	v_div_scale_f32 v60, s[8:9], v22, v26, v22
	v_fmac_f32_e32 v63, v67, v63
	v_mul_f32_e32 v66, v58, v62
	v_fma_f32 v68, -v61, v64, 1.0
	v_mul_f32_e32 v67, v60, v63
	v_fma_f32 v69, -v57, v66, v58
	v_div_scale_f32 v65, s[10:11], v51, v29, v51
	v_fmac_f32_e32 v64, v68, v64
	v_fma_f32 v70, -v59, v67, v60
	v_fmac_f32_e32 v66, v69, v62
	v_mul_f32_e32 v68, v65, v64
	v_fmac_f32_e32 v67, v70, v63
	v_fma_f32 v57, -v57, v66, v58
	v_fma_f32 v71, -v61, v68, v65
	v_fma_f32 v58, -v59, v67, v60
	v_div_fmas_f32 v57, v57, v62, v66
	s_mov_b64 vcc, s[8:9]
	v_fmac_f32_e32 v68, v71, v64
	v_div_fixup_f32 v39, v57, v55, v39
	v_div_fmas_f32 v55, v58, v63, v67
	v_fma_f32 v59, -v61, v68, v65
	v_div_fixup_f32 v22, v55, v26, v22
	s_mov_b64 vcc, s[10:11]
	v_mul_f32_e32 v19, v19, v22
	v_div_fmas_f32 v22, v59, v64, v68
	v_add_f32_e32 v26, 1.0, v56
	v_div_fixup_f32 v22, v22, v29, v51
	v_div_scale_f32 v29, s[4:5], v26, v26, v23
	v_mul_f32_e32 v20, v36, v20
	v_rcp_f32_e32 v36, v29
	v_mul_f32_e32 v20, v20, v22
	v_mul_f32_e32 v18, v18, v39
	v_mul_f32_e32 v16, v16, v21
	v_fma_f32 v17, -v29, v36, 1.0
	v_fmac_f32_e32 v36, v17, v36
	v_div_scale_f32 v17, vcc, v23, v26, v23
	v_mul_f32_e32 v22, v17, v36
	v_fma_f32 v39, -v29, v22, v17
	v_fmac_f32_e32 v22, v39, v36
	v_fma_f32 v17, -v29, v22, v17
	v_div_fmas_f32 v17, v17, v36, v22
	v_div_fixup_f32 v17, v17, v26, v23
	v_mul_f32_e32 v17, v16, v17
	v_cvt_pk_bf16_f32 v16, v18, v19
	v_mad_i64_i32 v[18:19], s[4:5], v54, s64, v[44:45]
	v_lshl_add_u64 v[18:19], v[18:19], 0, s[36:37]
	v_cvt_pk_bf16_f32 v17, v20, v17
	v_lshl_add_u64 v[20:21], v[18:19], 0, v[48:49]
	v_add_co_u32_e32 v18, vcc, s80, v20
	global_store_dwordx2 v[52:53], v[16:17], off offset:32
	s_nop 0
	v_addc_co_u32_e32 v19, vcc, 0, v21, vcc
	v_mov_b64_e32 v[22:23], v[140:141]
	v_cmp_gt_f32_e32 vcc, s79, v9
	v_mov_b64_e32 v[16:17], v[156:157]
	v_mov_b64_e32 v[18:19], v[158:159]
	v_and_b32_e32 v15, 0xffff0000, v22
	v_cndmask_b32_e32 v9, v9, v10, vcc
	v_rsq_f32_e32 v9, v9
	v_lshl_add_u64 v[10:11], v[20:21], 0, s[42:43]
	v_lshlrev_b32_e32 v20, 16, v23
	v_and_b32_e32 v21, 0xffff0000, v23
	v_mul_f32_e32 v14, 0x45800000, v9
	v_cndmask_b32_e32 v9, v9, v14, vcc
	v_lshlrev_b32_e32 v14, 16, v22
	v_mul_f32_e32 v22, 0xbfb8aa3b, v14
	v_mul_f32_e32 v12, v12, v9
	v_mul_f32_e32 v23, 0xbfb8aa3b, v15
	v_mul_f32_e32 v26, 0xbfb8aa3b, v20
	v_exp_f32_e32 v22, v22
	v_mul_f32_e32 v12, v12, v16
	v_exp_f32_e32 v16, v23
	v_exp_f32_e32 v23, v26
	v_mul_f32_e32 v13, v13, v9
	v_mul_f32_e32 v13, v13, v17
	v_add_f32_e32 v17, 1.0, v22
	v_add_f32_e32 v16, 1.0, v16
	v_add_f32_e32 v22, 1.0, v23
	v_div_scale_f32 v23, s[4:5], v17, v17, v14
	v_div_scale_f32 v29, s[4:5], v16, v16, v15
	v_rcp_f32_e32 v39, v23
	v_rcp_f32_e32 v42, v29
	v_div_scale_f32 v26, vcc, v14, v17, v14
	v_fma_f32 v51, -v23, v39, 1.0
	v_fma_f32 v52, -v29, v42, 1.0
	v_fmac_f32_e32 v39, v51, v39
	v_div_scale_f32 v36, s[8:9], v15, v16, v15
	v_fmac_f32_e32 v42, v52, v42
	v_mul_f32_e32 v51, v26, v39
	v_div_scale_f32 v46, s[4:5], v22, v22, v20
	v_mul_f32_e32 v52, v36, v42
	v_fma_f32 v53, -v23, v51, v26
	v_rcp_f32_e32 v47, v46
	v_fma_f32 v55, -v29, v52, v36
; __device__ __forceinline__ unsigned cvt_pk_bf16(float lo, float hi) { unsigned r; asm volatile("v_cvt_pk_bf16_f32 %0, %1, %2" : "=v"(r) : "v"(lo), "v"(hi)); return r; }
; __device__ __forceinline__ float bflo(unsigned v) { return __uint_as_float(v << 16); }
; __device__ __forceinline__ float bfhi(unsigned v) { return __uint_as_float(v & 0xffff0000u); }
; __device__ __forceinline__ void ret_stepC(const Params& p, unsigned char* smem, int u) {
;     ...
;     bf16_t* yb = (bf16_t*)(p.ws + WS_Y) + tok0 * DM;
; #pragma unroll
;     for (int m = 0; m < 4; ++m)
; #pragma unroll
;         for (int nn = 0; nn < 2; ++nn) {
;             const int c = wr * 64 + m * 16 + fr, e = wc * 32 + nn * 16 + fq * 4;
;             const u32x2 graw = *(const u32x2*)(proj + (size_t)c * INP + C_RG + h * 128 + e);
;             const f32x4 beta = *(const f32x4*)(p.ret_beta + h * 128 + e);
;             const float g[4] = {bflo(graw.x), bfhi(graw.x), bflo(graw.y), bfhi(graw.y)};
;             float y[4];
; #pragma unroll
;             for (int j = 0; j < 4; ++j) { const float on = (a1[m][nn][j] - mean[m]) * rstd[m]; const float sg = g[j] / (1.0f + __expf(-g[j])); y[j] = sg * (on * beta[j]); }
;             u32x2 w; w.x = cvt_pk_bf16(y[0], y[1]); w.y = cvt_pk_bf16(y[2], y[3]);
;             *(u32x2*)(yb + (size_t)c * DM + h * 128 + e) = w;
	v_fmac_f32_e32 v51, v53, v39
	v_fmac_f32_e32 v52, v55, v42
	v_fma_f32 v23, -v23, v51, v26
	v_fma_f32 v26, -v29, v52, v36
	v_div_fmas_f32 v23, v23, v39, v51
	s_mov_b64 vcc, s[8:9]
	v_div_fixup_f32 v14, v23, v17, v14
	v_div_fmas_f32 v17, v26, v42, v52
	v_mul_f32_e32 v12, v12, v14
	v_div_fixup_f32 v14, v17, v16, v15
	v_fma_f32 v15, -v46, v47, 1.0
	v_fmac_f32_e32 v47, v15, v47
	v_div_scale_f32 v15, vcc, v20, v22, v20
	v_mul_f32_e32 v16, v15, v47
	v_fma_f32 v17, -v46, v16, v15
	v_fmac_f32_e32 v16, v17, v47
	v_mul_f32_e32 v17, 0xbfb8aa3b, v21
	v_exp_f32_e32 v17, v17
	v_fma_f32 v15, -v46, v16, v15
	v_mul_f32_e32 v13, v13, v14
	v_sub_f32_e32 v14, v43, v8
	v_div_fmas_f32 v15, v15, v47, v16
	v_add_f32_e32 v16, 1.0, v17
	v_mul_f32_e32 v14, v14, v9
	v_div_scale_f32 v17, s[4:5], v16, v16, v21
	v_mul_f32_e32 v14, v14, v18
	v_rcp_f32_e32 v18, v17
	v_div_fixup_f32 v15, v15, v22, v20
	v_mul_f32_e32 v14, v14, v15
	v_sub_f32_e32 v15, v41, v8
	v_fma_f32 v20, -v17, v18, 1.0
	v_fmac_f32_e32 v18, v20, v18
	v_div_scale_f32 v20, vcc, v21, v16, v21
	v_mul_f32_e32 v22, v20, v18
	v_fma_f32 v23, -v17, v22, v20
	v_fmac_f32_e32 v22, v23, v18
	v_fma_f32 v17, -v17, v22, v20
	v_mul_f32_e32 v15, v15, v9
	v_div_fmas_f32 v17, v17, v18, v22
	v_div_fixup_f32 v16, v17, v16, v21
	v_mul_f32_e32 v15, v15, v19
	v_mul_f32_e32 v15, v15, v16
	v_ashrrev_i32_e32 v55, 31, v54
	v_cvt_pk_bf16_f32 v12, v12, v13
	v_cvt_pk_bf16_f32 v13, v14, v15
	v_mov_b64_e32 v[14:15], v[142:143]
	v_lshlrev_b64 v[10:11], 12, v[54:55]
	v_lshl_add_u64 v[10:11], s[14:15], 0, v[10:11]
	v_lshl_add_u64 v[16:17], v[10:11], 0, v[48:49]
	global_store_dwordx2 v[16:17], v[12:13], off
	v_mov_b64_e32 v[10:11], v[160:161]
	v_mov_b64_e32 v[12:13], v[162:163]
	v_sub_f32_e32 v18, v40, v8
	v_mul_f32_e32 v18, v18, v9
	v_sub_f32_e32 v19, v38, v8
	v_mul_f32_e32 v19, v19, v9
	v_sub_f32_e32 v20, v37, v8
	v_mul_f32_e32 v20, v20, v9
	v_sub_f32_e32 v8, v34, v8
	v_mul_f32_e32 v8, v8, v9
	v_lshlrev_b32_e32 v21, 16, v14
	v_and_b32_e32 v14, 0xffff0000, v14
	v_lshlrev_b32_e32 v22, 16, v15
	v_mul_f32_e32 v23, 0xbfb8aa3b, v21
	v_mul_f32_e32 v26, 0xbfb8aa3b, v14
	v_mul_f32_e32 v29, 0xbfb8aa3b, v22
	v_exp_f32_e32 v23, v23
	v_mul_f32_e32 v10, v18, v10
	v_exp_f32_e32 v18, v26
	v_exp_f32_e32 v26, v29
	v_mul_f32_e32 v11, v19, v11
	v_add_f32_e32 v19, 1.0, v23
	v_add_f32_e32 v18, 1.0, v18
	v_add_f32_e32 v23, 1.0, v26
	v_div_scale_f32 v26, s[4:5], v19, v19, v21
	v_div_scale_f32 v36, s[4:5], v18, v18, v14
	v_rcp_f32_e32 v39, v26
	v_rcp_f32_e32 v40, v36
	v_div_scale_f32 v29, vcc, v21, v19, v21
	v_fma_f32 v43, -v26, v39, 1.0
	v_fma_f32 v46, -v36, v40, 1.0
	v_fmac_f32_e32 v39, v43, v39
	v_div_scale_f32 v37, s[8:9], v14, v18, v14
	v_fmac_f32_e32 v40, v46, v40
	v_mul_f32_e32 v43, v29, v39
	v_mul_f32_e32 v46, v37, v40
	v_fma_f32 v51, -v26, v43, v29
	v_fma_f32 v52, -v36, v46, v37
	v_fmac_f32_e32 v43, v51, v39
	v_fmac_f32_e32 v46, v52, v40
	v_fma_f32 v26, -v26, v43, v29
	v_fma_f32 v29, -v36, v46, v37
	v_div_fmas_f32 v26, v26, v39, v43
	s_mov_b64 vcc, s[8:9]
	v_and_b32_e32 v15, 0xffff0000, v15
	v_div_fixup_f32 v19, v26, v19, v21
	v_div_fmas_f32 v21, v29, v40, v46
	v_div_scale_f32 v38, s[4:5], v23, v23, v22
	v_div_fixup_f32 v14, v21, v18, v14
	v_mul_f32_e32 v18, 0xbfb8aa3b, v15
	v_rcp_f32_e32 v41, v38
	v_exp_f32_e32 v18, v18
	v_div_scale_f32 v42, s[10:11], v22, v23, v22
	v_fma_f32 v47, -v38, v41, 1.0
	v_add_f32_e32 v18, 1.0, v18
	v_fmac_f32_e32 v41, v47, v41
	v_mul_f32_e32 v10, v10, v19
	v_div_scale_f32 v19, s[4:5], v18, v18, v15
	v_mul_f32_e32 v47, v42, v41
	v_mul_f32_e32 v12, v20, v12
	v_rcp_f32_e32 v20, v19
	v_mul_f32_e32 v11, v11, v14
	v_fma_f32 v14, -v38, v47, v42
	v_fmac_f32_e32 v47, v14, v41
	v_fma_f32 v14, -v38, v47, v42
	s_mov_b64 vcc, s[10:11]
	v_div_fmas_f32 v14, v14, v41, v47
	v_fma_f32 v9, -v19, v20, 1.0
	v_div_fixup_f32 v14, v14, v23, v22
	v_fmac_f32_e32 v20, v9, v20
	v_div_scale_f32 v9, vcc, v15, v18, v15
	v_mul_f32_e32 v12, v12, v14
	v_mul_f32_e32 v14, v9, v20
	v_fma_f32 v21, -v19, v14, v9
	v_fmac_f32_e32 v14, v21, v20
	v_fma_f32 v9, -v19, v14, v9
	v_div_fmas_f32 v9, v9, v20, v14
	v_div_fixup_f32 v9, v9, v18, v15
	v_mul_f32_e32 v8, v8, v13
	v_mul_f32_e32 v9, v8, v9
	v_cvt_pk_bf16_f32 v8, v10, v11
	v_mad_i64_i32 v[10:11], s[4:5], v50, s64, v[44:45]
	v_lshl_add_u64 v[10:11], v[10:11], 0, s[36:37]
	v_cvt_pk_bf16_f32 v9, v12, v9
	v_lshl_add_u64 v[12:13], v[10:11], 0, v[48:49]
	v_add_co_u32_e32 v10, vcc, s80, v12
	global_store_dwordx2 v[16:17], v[8:9], off offset:32
	s_nop 0
	v_addc_co_u32_e32 v11, vcc, 0, v13, vcc
	v_mov_b64_e32 v[14:15], v[144:145]
	v_cmp_gt_f32_e32 vcc, s79, v1
	v_mov_b64_e32 v[8:9], v[156:157]
	v_mov_b64_e32 v[10:11], v[158:159]
	v_ashrrev_i32_e32 v51, 31, v50
	v_cndmask_b32_e32 v1, v1, v2, vcc
	v_rsq_f32_e32 v1, v1
	v_lshl_add_u64 v[2:3], v[12:13], 0, s[42:43]
	v_mul_f32_e32 v6, 0x45800000, v1
	v_cndmask_b32_e32 v1, v1, v6, vcc
	v_mul_f32_e32 v4, v4, v1
	v_mul_f32_e32 v5, v5, v1
	v_lshlrev_b32_e32 v6, 16, v14
	v_and_b32_e32 v7, 0xffff0000, v14
	v_mul_f32_e32 v14, 0xbfb8aa3b, v6
; __device__ __forceinline__ unsigned cvt_pk_bf16(float lo, float hi) { unsigned r; asm volatile("v_cvt_pk_bf16_f32 %0, %1, %2" : "=v"(r) : "v"(lo), "v"(hi)); return r; }
; __device__ __forceinline__ float bflo(unsigned v) { return __uint_as_float(v << 16); }
; __device__ __forceinline__ float bfhi(unsigned v) { return __uint_as_float(v & 0xffff0000u); }
; __device__ __forceinline__ void ret_stepC(const Params& p, unsigned char* smem, int u) {
;     ...
;     bf16_t* yb = (bf16_t*)(p.ws + WS_Y) + tok0 * DM;
; #pragma unroll
;     for (int m = 0; m < 4; ++m)
; #pragma unroll
;         for (int nn = 0; nn < 2; ++nn) {
;             const int c = wr * 64 + m * 16 + fr, e = wc * 32 + nn * 16 + fq * 4;
;             const u32x2 graw = *(const u32x2*)(proj + (size_t)c * INP + C_RG + h * 128 + e);
;             const f32x4 beta = *(const f32x4*)(p.ret_beta + h * 128 + e);
;             const float g[4] = {bflo(graw.x), bfhi(graw.x), bflo(graw.y), bfhi(graw.y)};
;             float y[4];
; #pragma unroll
;             for (int j = 0; j < 4; ++j) { const float on = (a1[m][nn][j] - mean[m]) * rstd[m]; const float sg = g[j] / (1.0f + __expf(-g[j])); y[j] = sg * (on * beta[j]); }
;             u32x2 w; w.x = cvt_pk_bf16(y[0], y[1]); w.y = cvt_pk_bf16(y[2], y[3]);
;             *(u32x2*)(yb + (size_t)c * DM + h * 128 + e) = w;
	v_lshlrev_b32_e32 v12, 16, v15
	v_and_b32_e32 v13, 0xffff0000, v15
	v_mul_f32_e32 v15, 0xbfb8aa3b, v7
	v_exp_f32_e32 v14, v14
	v_exp_f32_e32 v15, v15
	v_mul_f32_e32 v16, 0xbfb8aa3b, v12
	v_mul_f32_e32 v4, v4, v8
	v_add_f32_e32 v14, 1.0, v14
	v_exp_f32_e32 v8, v16
	v_add_f32_e32 v15, 1.0, v15
	v_div_scale_f32 v16, s[4:5], v14, v14, v6
	v_div_scale_f32 v18, s[4:5], v15, v15, v7
	v_rcp_f32_e32 v19, v16
	v_rcp_f32_e32 v20, v18
	v_div_scale_f32 v17, vcc, v6, v14, v6
	v_fma_f32 v22, -v16, v19, 1.0
	v_fma_f32 v23, -v18, v20, 1.0
	v_fmac_f32_e32 v19, v22, v19
	v_div_scale_f32 v21, s[8:9], v7, v15, v7
	v_fmac_f32_e32 v20, v23, v20
	v_mul_f32_e32 v22, v17, v19
	v_mul_f32_e32 v23, v21, v20
	v_fma_f32 v26, -v16, v22, v17
	v_fma_f32 v29, -v18, v23, v21
	v_fmac_f32_e32 v22, v26, v19
	v_fmac_f32_e32 v23, v29, v20
	v_fma_f32 v16, -v16, v22, v17
	v_fma_f32 v17, -v18, v23, v21
	v_div_fmas_f32 v16, v16, v19, v22
	s_mov_b64 vcc, s[8:9]
	v_div_fixup_f32 v6, v16, v14, v6
	v_div_fmas_f32 v14, v17, v20, v23
	v_mul_f32_e32 v4, v4, v6
	v_div_fixup_f32 v6, v14, v15, v7
	v_add_f32_e32 v7, 1.0, v8
	v_div_scale_f32 v8, s[4:5], v7, v7, v12
	v_mul_f32_e32 v5, v5, v9
	v_rcp_f32_e32 v9, v8
	v_mul_f32_e32 v5, v5, v6
	v_sub_f32_e32 v6, v33, v0
	v_mul_f32_e32 v6, v6, v1
	v_fma_f32 v14, -v8, v9, 1.0
	v_fmac_f32_e32 v9, v14, v9
	v_div_scale_f32 v14, vcc, v12, v7, v12
	v_mul_f32_e32 v15, v14, v9
	v_fma_f32 v16, -v8, v15, v14
	v_fmac_f32_e32 v15, v16, v9
	v_fma_f32 v8, -v8, v15, v14
	v_mul_f32_e32 v14, 0xbfb8aa3b, v13
	v_exp_f32_e32 v14, v14
	v_div_fmas_f32 v8, v8, v9, v15
	v_div_fixup_f32 v7, v8, v7, v12
	v_mul_f32_e32 v6, v6, v10
	v_add_f32_e32 v8, 1.0, v14
	v_div_scale_f32 v9, s[4:5], v8, v8, v13
	v_rcp_f32_e32 v10, v9
	v_mul_f32_e32 v6, v6, v7
	v_sub_f32_e32 v7, v31, v0
	v_mul_f32_e32 v7, v7, v1
	v_fma_f32 v12, -v9, v10, 1.0
	v_fmac_f32_e32 v10, v12, v10
	v_div_scale_f32 v12, vcc, v13, v8, v13
	v_mul_f32_e32 v14, v12, v10
	v_fma_f32 v15, -v9, v14, v12
	v_fmac_f32_e32 v14, v15, v10
	v_fma_f32 v9, -v9, v14, v12
	v_div_fmas_f32 v9, v9, v10, v14
	v_div_fixup_f32 v8, v9, v8, v13
	v_mul_f32_e32 v7, v7, v11
	v_mul_f32_e32 v7, v7, v8
	v_cvt_pk_bf16_f32 v4, v4, v5
	v_cvt_pk_bf16_f32 v5, v6, v7
	v_mov_b64_e32 v[6:7], v[146:147]
	v_lshlrev_b64 v[2:3], 12, v[50:51]
	v_lshl_add_u64 v[2:3], s[14:15], 0, v[2:3]
	v_lshl_add_u64 v[8:9], v[2:3], 0, v[48:49]
	global_store_dwordx2 v[8:9], v[4:5], off
	v_mov_b64_e32 v[2:3], v[160:161]
	v_mov_b64_e32 v[4:5], v[162:163]
	v_sub_f32_e32 v10, v30, v0
	v_mul_f32_e32 v10, v10, v1
	v_sub_f32_e32 v11, v28, v0
	v_mul_f32_e32 v11, v11, v1
	v_sub_f32_e32 v12, v27, v0
	v_mul_f32_e32 v12, v12, v1
	v_sub_f32_e32 v0, v24, v0
	v_mul_f32_e32 v0, v0, v1
	v_lshlrev_b32_e32 v13, 16, v6
	v_and_b32_e32 v6, 0xffff0000, v6
	v_lshlrev_b32_e32 v14, 16, v7
	v_mul_f32_e32 v15, 0xbfb8aa3b, v13
	v_mul_f32_e32 v16, 0xbfb8aa3b, v6
	v_mul_f32_e32 v17, 0xbfb8aa3b, v14
	v_exp_f32_e32 v15, v15
	v_mul_f32_e32 v2, v10, v2
	v_exp_f32_e32 v10, v16
	v_exp_f32_e32 v16, v17
	v_mul_f32_e32 v3, v11, v3
	v_add_f32_e32 v11, 1.0, v15
	v_add_f32_e32 v10, 1.0, v10
	v_add_f32_e32 v15, 1.0, v16
	v_div_scale_f32 v16, s[4:5], v11, v11, v13
	v_div_scale_f32 v18, s[4:5], v10, v10, v6
	v_rcp_f32_e32 v20, v16
	v_rcp_f32_e32 v21, v18
	v_div_scale_f32 v17, vcc, v13, v11, v13
	v_fma_f32 v25, -v16, v20, 1.0
	v_fma_f32 v26, -v18, v21, 1.0
	v_fmac_f32_e32 v20, v25, v20
	v_div_scale_f32 v19, s[8:9], v6, v10, v6
	v_fmac_f32_e32 v21, v26, v21
	v_mul_f32_e32 v25, v17, v20
	v_mul_f32_e32 v26, v19, v21
	v_fma_f32 v27, -v16, v25, v17
	v_div_scale_f32 v22, s[4:5], v15, v15, v14
	v_fma_f32 v28, -v18, v26, v19
	v_fmac_f32_e32 v25, v27, v20
	v_rcp_f32_e32 v23, v22
	v_fmac_f32_e32 v26, v28, v21
	v_fma_f32 v16, -v16, v25, v17
	v_fma_f32 v17, -v18, v26, v19
	v_div_fmas_f32 v16, v16, v20, v25
	s_mov_b64 vcc, s[8:9]
	v_div_fixup_f32 v11, v16, v11, v13
	v_div_fmas_f32 v13, v17, v21, v26
	v_div_fixup_f32 v6, v13, v10, v6
	v_mul_f32_e32 v3, v3, v6
	v_fma_f32 v6, -v22, v23, 1.0
	v_fmac_f32_e32 v23, v6, v23
	v_div_scale_f32 v6, vcc, v14, v15, v14
	v_mul_f32_e32 v10, v6, v23
	v_and_b32_e32 v7, 0xffff0000, v7
	v_mul_f32_e32 v2, v2, v11
	v_fma_f32 v11, -v22, v10, v6
	v_fmac_f32_e32 v10, v11, v23
	v_mul_f32_e32 v11, 0xbfb8aa3b, v7
	v_exp_f32_e32 v11, v11
	v_fma_f32 v6, -v22, v10, v6
	v_div_fmas_f32 v6, v6, v23, v10
	v_mul_f32_e32 v4, v12, v4
	v_add_f32_e32 v10, 1.0, v11
	v_div_scale_f32 v11, s[4:5], v10, v10, v7
	v_rcp_f32_e32 v12, v11
	v_div_fixup_f32 v6, v6, v15, v14
	v_mul_f32_e32 v4, v4, v6
	v_mul_f32_e32 v0, v0, v5
	v_fma_f32 v1, -v11, v12, 1.0
	v_fmac_f32_e32 v12, v1, v12
	v_div_scale_f32 v1, vcc, v7, v10, v7
	v_mul_f32_e32 v6, v1, v12
	v_fma_f32 v13, -v11, v6, v1
	v_fmac_f32_e32 v6, v13, v12
	v_fma_f32 v1, -v11, v6, v1
	v_div_fmas_f32 v1, v1, v12, v6
	v_div_fixup_f32 v1, v1, v10, v7
	v_mul_f32_e32 v1, v0, v1
	v_cvt_pk_bf16_f32 v0, v2, v3
	v_cvt_pk_bf16_f32 v1, v4, v1
	global_store_dwordx2 v[8:9], v[0:1], off offset:32
	s_barrier
	s_cbranch_scc1 .LBB0_1718
